# P1 tile order: the second m-group of each XCD takes its column tiles rotated by 6, so every workgroup gets exactly one V tile (slow transposed 2-byte-store epilogue) instead of two or none
# speedup vs baseline: 1.0186x; 1.0076x over previous
;     __host__ __device__ bool next(int i, Unit& u) const {
;         const long L = (long)i * G + c; if (L >= nwg) return false;
;         int wgid = (int)L; { const int q = nwg / NXCD, r = nwg % NXCD, xcd = wgid % NXCD, off = wgid / NXCD; wgid = (xcd < r ? xcd * (q + 1) : r * (q + 1) + (xcd - r) * q) + off; }
;         const int nig = WGM * nN, gid = wgid / nig, fm = gid * WGM, gsz = (nM - fm) < WGM ? (nM - fm) : WGM;
;         u.pm = fm + ((wgid % nig) % gsz); u.pn = (wgid % nig) / gsz; return true;
;     }
.LBB0_424:
	s_add_i32 s97, s97, 1
	s_mul_i32 s2, s97, s71
	s_mul_hi_u32 s3, s97, s89
	s_add_i32 s3, s3, s2
	s_mul_i32 s2, s97, s89
	s_add_u32 s24, s2, s33
	s_addc_u32 s25, s3, s78
	v_cmp_gt_i64_e32 vcc, s[24:25], v[146:147]
	v_cmp_lt_i64_e64 s[2:3], s[24:25], v[144:145]
	s_cbranch_vccnz .LBB0_426
	s_ashr_i32 s5, s24, 31
	s_lshr_b32 s5, s5, 29
	s_add_i32 s5, s24, s5
	s_ashr_i32 s7, s5, 3
	s_and_b32 s5, s5, -8
	s_sub_i32 s5, s24, s5
	s_cmp_lt_i32 s5, 0
	s_movk_i32 s12, 0xc1
	s_cselect_b32 s12, s12, 0xc0
	s_mul_i32 s5, s5, s12
	s_add_i32 s5, s5, s7
	s_mul_hi_i32 s7, s5, 0x2aaaaaab
	s_lshr_b32 s12, s7, 31
	s_ashr_i32 s7, s7, 4
	s_add_i32 s7, s7, s12
	s_lshl_b32 s12, s7, 3
	s_sub_i32 s20, 0x80, s12
	s_min_i32 s21, s20, 8
	s_abs_i32 s20, s21
	v_cvt_f32_u32_e32 v0, s20
	s_sub_i32 s23, 0, s20
	s_mulk_i32 s7, 0x60
	s_sub_i32 s5, s5, s7
	s_bitcmp1_b32 s12, 3
	s_cselect_b32 s98, 48, 0
	s_add_i32 s5, s5, s98
	s_cmpk_gt_i32 s5, 0x5f
	s_cselect_b32 s98, 0x60, 0
	s_sub_i32 s5, s5, s98
	s_nop 0
	s_nop 0
	s_nop 0
	s_nop 0
	s_nop 0
	s_nop 0
	s_nop 0
	s_nop 0
	s_nop 0
	v_rcp_iflag_f32_e32 v0, v0
	s_abs_i32 s7, s5
	s_xor_b32 s22, s5, s21
	s_ashr_i32 s22, s22, 31
	v_mul_f32_e32 v0, 0x4f7ffffe, v0
	v_cvt_u32_f32_e32 v0, v0
	s_nop 0
	v_readfirstlane_b32 s24, v0
	s_mul_i32 s23, s23, s24
	s_mul_hi_u32 s23, s24, s23
	s_add_i32 s24, s24, s23
	s_mul_hi_u32 s23, s7, s24
	s_mul_i32 s24, s23, s20
	s_sub_i32 s7, s7, s24
	s_add_i32 s25, s23, 1
	s_sub_i32 s24, s7, s20
	s_cmp_ge_u32 s7, s20
	s_cselect_b32 s23, s25, s23
	s_cselect_b32 s7, s24, s7
	s_add_i32 s24, s23, 1
	s_cmp_ge_u32 s7, s20
	s_cselect_b32 s7, s24, s23
	s_xor_b32 s7, s7, s22
	s_sub_i32 s20, s7, s22
	s_mul_i32 s7, s20, s21
	s_sub_i32 s5, s5, s7
	s_add_i32 s22, s12, s5
